# norm phases: per-batch gamma*(1+scale)/shift reload issues all 16 loads then one wait (was 8 serial load-wait groups), shift loads covered by a counted wait in the row body
# speedup vs baseline: 1.0009x; 1.0009x over previous
; template <int MODE, bool XBF> DI void norm_phase(const void* Xv, const bf16_t* Y, bf16_t* xr_out, float* xout, const float* __restrict__ lnw, const float* __restrict__ modl  , int sh_off, int sc_off, bf16_t* out_bf, int gw, int NGW, int lane) {
;     ...
;         const int b = m / T;
;         if (b != curb) { curb = b;
; #pragma unroll
;             for (int j = 0; j < 8; ++j) { const int k = 4 * (lane + 64 * j); const f32x4 g = *(const f32x4*)(lnw + k);
;                 if (MODE == 0) { const f32x4 sc = *(const f32x4*)(modl + b * NMOD + sc_off + k); A[j] = g * (sc + 1.0f); B[j] = *(const f32x4*)(modl + b * NMOD + sh_off + k); } else { A[j] = g; B[j] = (f32x4){0.f, 0.f, 0.f, 0.f}; } } }
.LBB0_160:
	s_ashr_i32 s0, s36, 31
	s_lshr_b32 s0, s0, 19
	s_add_i32 s0, s36, s0
	s_ashr_i32 s12, s0, 13
	s_cmp_eq_u32 s12, s11
	s_cbranch_scc1 .LBB0_162
	s_mul_i32 s0, s12, 0x3000
	s_ashr_i32 s1, s0, 31
	s_lshl_b64 s[0:1], s[0:1], 2
	v_readlane_b32 s8, v255, 0
	s_add_u32 s0, s8, s0
	v_readlane_b32 s8, v255, 1
	s_addc_u32 s1, s8, s1
	s_add_u32 s8, s0, 0x8000
	s_addc_u32 s9, s1, 0
	s_add_u32 s0, s0, 0x6000
	s_addc_u32 s1, s1, 0
	s_mov_b32 s11, s12
	s_nop 1
	global_load_dwordx4 v[20:23], v[130:131], off
	global_load_dwordx4 v[28:31], v191, s[8:9]
	global_load_dwordx4 v[40:43], v[130:131], off offset:1024
	global_load_dwordx4 v[44:47], v196, s[8:9]
	global_load_dwordx4 v[48:51], v[130:131], off offset:2048
	global_load_dwordx4 v[52:55], v197, s[8:9]
	global_load_dwordx4 v[56:59], v[130:131], off offset:3072
	global_load_dwordx4 v[60:63], v198, s[8:9]
	global_load_dwordx4 v[72:75], v[132:133], off
	global_load_dwordx4 v[76:79], v199, s[8:9]
	global_load_dwordx4 v[88:91], v[134:135], off
	global_load_dwordx4 v[98:101], v200, s[8:9]
	global_load_dwordx4 v[106:109], v[136:137], off
	global_load_dwordx4 v[114:117], v201, s[8:9]
	global_load_dwordx4 v[122:125], v[138:139], off
	global_load_dwordx4 v[126:129], v202, s[8:9]
	s_waitcnt vmcnt(0)
	v_pk_add_f32 v[30:31], v[30:31], 1.0 op_sel_hi:[1,0]
	v_pk_add_f32 v[28:29], v[28:29], 1.0 op_sel_hi:[1,0]
	v_pk_mul_f32 v[22:23], v[22:23], v[30:31]
	v_pk_mul_f32 v[20:21], v[20:21], v[28:29]
	v_pk_add_f32 v[46:47], v[46:47], 1.0 op_sel_hi:[1,0]
	v_pk_add_f32 v[44:45], v[44:45], 1.0 op_sel_hi:[1,0]
	v_pk_mul_f32 v[42:43], v[42:43], v[46:47]
	v_pk_mul_f32 v[40:41], v[40:41], v[44:45]
	v_pk_add_f32 v[54:55], v[54:55], 1.0 op_sel_hi:[1,0]
	v_pk_add_f32 v[52:53], v[52:53], 1.0 op_sel_hi:[1,0]
	v_pk_mul_f32 v[50:51], v[50:51], v[54:55]
	v_pk_mul_f32 v[48:49], v[48:49], v[52:53]
	v_pk_add_f32 v[62:63], v[62:63], 1.0 op_sel_hi:[1,0]
	v_pk_add_f32 v[60:61], v[60:61], 1.0 op_sel_hi:[1,0]
	v_pk_mul_f32 v[58:59], v[58:59], v[62:63]
	v_pk_mul_f32 v[56:57], v[56:57], v[60:61]
	v_pk_add_f32 v[78:79], v[78:79], 1.0 op_sel_hi:[1,0]
	v_pk_add_f32 v[76:77], v[76:77], 1.0 op_sel_hi:[1,0]
	v_pk_mul_f32 v[74:75], v[74:75], v[78:79]
	v_pk_mul_f32 v[72:73], v[72:73], v[76:77]
	v_pk_add_f32 v[100:101], v[100:101], 1.0 op_sel_hi:[1,0]
	v_pk_add_f32 v[98:99], v[98:99], 1.0 op_sel_hi:[1,0]
	v_pk_mul_f32 v[90:91], v[90:91], v[100:101]
	v_pk_mul_f32 v[88:89], v[88:89], v[98:99]
	v_pk_add_f32 v[116:117], v[116:117], 1.0 op_sel_hi:[1,0]
	v_pk_add_f32 v[114:115], v[114:115], 1.0 op_sel_hi:[1,0]
	v_pk_mul_f32 v[108:109], v[108:109], v[116:117]
	v_pk_mul_f32 v[106:107], v[106:107], v[114:115]
	v_pk_add_f32 v[128:129], v[128:129], 1.0 op_sel_hi:[1,0]
	v_pk_add_f32 v[126:127], v[126:127], 1.0 op_sel_hi:[1,0]
	v_pk_mul_f32 v[124:125], v[124:125], v[128:129]
	v_pk_mul_f32 v[122:123], v[122:123], v[126:127]
	global_load_dwordx4 v[28:31], v191, s[0:1]
	global_load_dwordx4 v[44:47], v196, s[0:1]
	global_load_dwordx4 v[52:55], v197, s[0:1]
	global_load_dwordx4 v[60:63], v198, s[0:1]
	global_load_dwordx4 v[76:79], v199, s[0:1]
	global_load_dwordx4 v[98:101], v200, s[0:1]
	global_load_dwordx4 v[114:117], v201, s[0:1]
	global_load_dwordx4 v[126:129], v202, s[0:1]

; #define NP_LOAD(V, XB, YV, ROW) do { _Pragma("unroll") for (int j = 0; j < 8; ++j) { \
;         if (XBF) XB[j] = ((gcy)((const bf16_t*)Xv + (size_t)(ROW) * D) + lane)[64 * j]; else V[j] = ((gcp)((const float*)Xv + (size_t)(ROW) * D) + lane)[64 * j]; \
;         if (Y) YV[j] = ((gcy)(Y + (size_t)(ROW) * D) + lane)[64 * j]; } } while (0)
; template <int MODE, bool XBF> DI void norm_phase(const void* Xv, const bf16_t* Y, bf16_t* xr_out, float* xout, const float* __restrict__ lnw, const float* __restrict__ modl  , int sh_off, int sc_off, bf16_t* out_bf, int gw, int NGW, int lane) {
;     ...
;         if (b != curb) { curb = b;
; #pragma unroll
;             for (int j = 0; j < 8; ++j) { const int k = 4 * (lane + 64 * j); const f32x4 g = *(const f32x4*)(lnw + k);
;                 if (MODE == 0) { const f32x4 sc = *(const f32x4*)(modl + b * NMOD + sc_off + k); A[j] = g * (sc + 1.0f); B[j] = *(const f32x4*)(modl + b * NMOD + sh_off + k); } else { A[j] = g; B[j] = (f32x4){0.f, 0.f, 0.f, 0.f}; } } }
;         if (m + 1 < m1) NP_LOAD(vn, xbn, yn, m + 1);
.LBB0_707:
	s_ashr_i32 s0, s5, 31
	s_lshr_b32 s0, s0, 19
	s_add_i32 s0, s5, s0
	s_ashr_i32 s12, s0, 13
	s_cmp_eq_u32 s12, s11
	s_cbranch_scc1 .LBB0_709
	s_mul_i32 s0, s12, 0x3000
	s_ashr_i32 s1, s0, 31
	s_lshl_b64 s[0:1], s[0:1], 2
	v_readlane_b32 s8, v255, 0
	s_add_u32 s0, s8, s0
	v_readlane_b32 s8, v255, 1
	s_addc_u32 s1, s8, s1
	s_add_u32 s8, s0, 0x2000
	s_addc_u32 s9, s1, 0
	s_mov_b32 s11, s12
	s_nop 1
	global_load_dwordx4 v[0:3], v[64:65], off
	global_load_dwordx4 v[4:7], v150, s[8:9]
	global_load_dwordx4 v[8:11], v[64:65], off offset:1024
	global_load_dwordx4 v[12:15], v151, s[8:9]
	global_load_dwordx4 v[16:19], v[64:65], off offset:2048
	global_load_dwordx4 v[20:23], v152, s[8:9]
	global_load_dwordx4 v[24:27], v[64:65], off offset:3072
	global_load_dwordx4 v[28:31], v153, s[8:9]
	global_load_dwordx4 v[32:35], v[66:67], off
	global_load_dwordx4 v[36:39], v154, s[8:9]
	global_load_dwordx4 v[40:43], v[68:69], off
	global_load_dwordx4 v[44:47], v155, s[8:9]
	global_load_dwordx4 v[48:51], v[70:71], off
	global_load_dwordx4 v[52:55], v156, s[8:9]
	global_load_dwordx4 v[56:59], v[72:73], off
	global_load_dwordx4 v[60:63], v157, s[8:9]
	s_waitcnt vmcnt(0)
	v_pk_add_f32 v[6:7], v[6:7], 1.0 op_sel_hi:[1,0]
	v_pk_add_f32 v[4:5], v[4:5], 1.0 op_sel_hi:[1,0]
	v_pk_mul_f32 v[2:3], v[2:3], v[6:7]
	v_pk_mul_f32 v[0:1], v[0:1], v[4:5]
	v_pk_add_f32 v[14:15], v[14:15], 1.0 op_sel_hi:[1,0]
	v_pk_add_f32 v[12:13], v[12:13], 1.0 op_sel_hi:[1,0]
	v_pk_mul_f32 v[14:15], v[10:11], v[14:15]
	v_pk_mul_f32 v[12:13], v[8:9], v[12:13]
	v_pk_add_f32 v[22:23], v[22:23], 1.0 op_sel_hi:[1,0]
	v_pk_add_f32 v[20:21], v[20:21], 1.0 op_sel_hi:[1,0]
	v_pk_mul_f32 v[22:23], v[18:19], v[22:23]
	v_pk_mul_f32 v[20:21], v[16:17], v[20:21]
	v_pk_add_f32 v[30:31], v[30:31], 1.0 op_sel_hi:[1,0]
	v_pk_add_f32 v[28:29], v[28:29], 1.0 op_sel_hi:[1,0]
	v_pk_mul_f32 v[30:31], v[26:27], v[30:31]
	v_pk_mul_f32 v[28:29], v[24:25], v[28:29]
	v_pk_add_f32 v[38:39], v[38:39], 1.0 op_sel_hi:[1,0]
	v_pk_add_f32 v[36:37], v[36:37], 1.0 op_sel_hi:[1,0]
	v_pk_mul_f32 v[38:39], v[34:35], v[38:39]
	v_pk_mul_f32 v[36:37], v[32:33], v[36:37]
	v_pk_add_f32 v[46:47], v[46:47], 1.0 op_sel_hi:[1,0]
	v_pk_add_f32 v[44:45], v[44:45], 1.0 op_sel_hi:[1,0]
	v_pk_mul_f32 v[46:47], v[42:43], v[46:47]
	v_pk_mul_f32 v[44:45], v[40:41], v[44:45]
	v_pk_add_f32 v[54:55], v[54:55], 1.0 op_sel_hi:[1,0]
	v_pk_add_f32 v[52:53], v[52:53], 1.0 op_sel_hi:[1,0]
	v_pk_mul_f32 v[54:55], v[50:51], v[54:55]
	v_pk_mul_f32 v[52:53], v[48:49], v[52:53]
	v_pk_add_f32 v[62:63], v[62:63], 1.0 op_sel_hi:[1,0]
	v_pk_add_f32 v[60:61], v[60:61], 1.0 op_sel_hi:[1,0]
	v_pk_mul_f32 v[58:59], v[58:59], v[62:63]
	v_pk_mul_f32 v[56:57], v[56:57], v[60:61]
	global_load_dwordx4 v[4:7], v150, s[0:1]
	global_load_dwordx4 v[8:11], v150, s[0:1] offset:1024
	global_load_dwordx4 v[16:19], v150, s[0:1] offset:2048
	global_load_dwordx4 v[24:27], v150, s[0:1] offset:3072
	global_load_dwordx4 v[32:35], v154, s[0:1]
	global_load_dwordx4 v[40:43], v155, s[0:1]
	global_load_dwordx4 v[48:51], v156, s[0:1]
	global_load_dwordx4 v[60:63], v157, s[0:1]
	s_add_i32 s0, s5, 1
	s_cmp_ge_i32 s0, s10
	s_cbranch_scc0 .Lrl_bb_708
	s_waitcnt vmcnt(0)
.Lrl_bb_708:
.LBB0_709:
	s_add_i32 s5, s5, 1
	s_cmp_ge_i32 s5, s10
	s_cselect_b64 s[8:9], -1, 0
	s_and_b64 vcc, exec, s[8:9]
	s_cbranch_vccnz .LBB0_706
	v_add_co_u32_e32 v84, vcc, 0xf800000, v74
	s_nop 1
	v_addc_co_u32_e32 v85, vcc, 0, v75, vcc
	global_load_dwordx2 v[92:93], v[84:85], off
	global_load_dwordx2 v[94:95], v[84:85], off offset:512
	global_load_dwordx2 v[98:99], v[84:85], off offset:1024
	global_load_dwordx2 v[100:101], v[84:85], off offset:1536
	global_load_dwordx2 v[82:83], v[74:75], off
	global_load_dwordx2 v[80:81], v[74:75], off offset:512
	global_load_dwordx2 v[78:79], v[74:75], off offset:1024
	global_load_dwordx2 v[76:77], v[74:75], off offset:1536
	global_load_dwordx2 v[102:103], v[84:85], off offset:2048
	global_load_dwordx2 v[104:105], v[84:85], off offset:2560
	global_load_dwordx2 v[106:107], v[84:85], off offset:3072
	global_load_dwordx2 v[108:109], v[84:85], off offset:3584
	global_load_dwordx2 v[90:91], v[74:75], off offset:2048
	global_load_dwordx2 v[88:89], v[74:75], off offset:2560
	global_load_dwordx2 v[86:87], v[74:75], off offset:3072
	s_nop 0
	global_load_dwordx2 v[84:85], v[74:75], off offset:3584
	s_branch .LBB0_706

; DI unsigned cvtpk(float lo, float hi) { f32x2 v = {lo, hi}; bf16x2_t b = __builtin_convertvector(v, bf16x2_t); return __builtin_bit_cast(unsigned, b); }
; DI float bflo(unsigned u) { return __uint_as_float(u << 16); }
; DI float bfhi(unsigned u) { return __uint_as_float(u & 0xffff0000u); }
; template <int MODE, bool XBF> DI void norm_phase(const void* Xv, const bf16_t* Y, bf16_t* xr_out, float* xout, const float* __restrict__ lnw, const float* __restrict__ modl  , int sh_off, int sc_off, bf16_t* out_bf, int gw, int NGW, int lane) {
;     ...
;         float s = 0.f;
; #pragma unroll
;         for (int j = 0; j < 8; ++j) { if (XBF) v[j] = (f32x4){bflo(xb[j].x), bfhi(xb[j].x), bflo(xb[j].y), bfhi(xb[j].y)};
;             if (Y) { v[j].x += bflo(yv[j].x); v[j].y += bfhi(yv[j].x); v[j].z += bflo(yv[j].y); v[j].w += bfhi(yv[j].y); }
;             s += (v[j].x * v[j].x + v[j].y * v[j].y) + (v[j].z * v[j].z + v[j].w * v[j].w); }
;         const float rstd = 1.0f / sqrtf(wave_sum(s) * (1.0f / D) + EPS);
;         if (MODE == 0) {
;             if (xr_out) { u32x2* xo = (u32x2*)(xr_out + (size_t)m * D) + lane;
; #pragma unroll
;                 for (int j = 0; j < 8; ++j) { u32x2 w; w.x = cvtpk(v[j].x, v[j].y); w.y = cvtpk(v[j].z, v[j].w); xo[64 * j] = w; } }
;             u32x2* o = (u32x2*)(out_bf + (size_t)m * D) + lane;
; #pragma unroll
;             for (int j = 0; j < 8; ++j) { const f32x4 y = v[j] * rstd * A[j] + B[j]; u32x2 w; w.x = cvtpk(y.x, y.y); w.y = cvtpk(y.z, y.w); o[64 * j] = w; }
.LBB0_715:
	v_pk_mul_f32 v[174:175], v[28:29], v[28:29]
	v_pk_mul_f32 v[176:177], v[24:25], v[24:25]
	v_pk_mul_f32 v[170:171], v[30:31], v[30:31]
	v_pk_mul_f32 v[172:173], v[26:27], v[26:27]
	v_mov_b32_e32 v178, v174
	v_mov_b32_e32 v179, v176
	v_mov_b32_e32 v176, v175
	v_pk_mul_f32 v[166:167], v[22:23], v[22:23]
	v_pk_mul_f32 v[168:169], v[20:21], v[20:21]
	v_pk_add_f32 v[174:175], v[178:179], v[176:177]
	v_mov_b32_e32 v176, v170
	v_mov_b32_e32 v177, v172
	v_mov_b32_e32 v172, v171
	v_pk_add_f32 v[170:171], v[176:177], v[172:173]
	v_pk_mov_b32 v[172:173], v[168:169], v[166:167] op_sel:[1,0]
	v_mov_b32_e32 v169, v167
	v_pk_add_f32 v[166:167], v[172:173], v[168:169]
	v_pk_add_f32 v[170:171], v[174:175], v[170:171]
	v_pk_add_f32 v[166:167], v[166:167], v[166:167] op_sel_hi:[0,1]
	v_mul_f32_e32 v166, v12, v12
	v_pk_fma_f32 v[168:169], v[12:13], v[12:13], v[166:167] op_sel_hi:[1,1,0]
	v_mul_f32_e32 v166, v14, v14
	v_pk_add_f32 v[170:171], v[170:171], v[170:171] op_sel_hi:[0,1]
	v_pk_fma_f32 v[172:173], v[14:15], v[14:15], v[166:167] op_sel_hi:[1,1,0]
	v_mul_f32_e32 v168, v16, v16
	v_mul_f32_e32 v172, v17, v17
	v_mul_f32_e32 v166, v18, v18
	v_mul_f32_e32 v170, v19, v19
	v_pk_mul_f32 v[162:163], v[10:11], v[10:11]
	v_pk_mul_f32 v[164:165], v[8:9], v[8:9]
	v_pk_add_f32 v[168:169], v[168:169], v[172:173]
	v_pk_add_f32 v[166:167], v[166:167], v[170:171]
	s_mov_b32 s0, 0xf800000
	v_pk_add_f32 v[166:167], v[168:169], v[166:167]
	v_pk_mov_b32 v[168:169], v[164:165], v[162:163] op_sel:[1,0]
	v_mov_b32_e32 v165, v163
	v_pk_add_f32 v[162:163], v[168:169], v[164:165]
	v_pk_add_f32 v[166:167], v[166:167], v[166:167] op_sel_hi:[0,1]
	v_pk_add_f32 v[162:163], v[162:163], v[162:163] op_sel_hi:[0,1]
	v_mul_f32_e32 v162, v4, v4
	v_pk_fma_f32 v[164:165], v[4:5], v[4:5], v[162:163] op_sel_hi:[1,1,0]
	v_mul_f32_e32 v162, v6, v6
	v_pk_fma_f32 v[168:169], v[6:7], v[6:7], v[162:163] op_sel_hi:[1,1,0]
	v_mul_f32_e32 v164, v96, v96
	v_mul_f32_e32 v168, v98, v98
	v_mul_f32_e32 v162, v99, v99
	v_mul_f32_e32 v166, v160, v160
	v_pk_add_f32 v[98:99], v[164:165], v[168:169]
	v_pk_add_f32 v[160:161], v[162:163], v[166:167]
	v_lshl_add_u64 v[144:145], v[144:145], 0, s[20:21]
	v_pk_add_f32 v[98:99], v[98:99], v[160:161]
	s_nop 0
	v_add_f32_e32 v96, v98, v99
	ds_bpermute_b32 v98, v146, v96
	s_waitcnt lgkmcnt(0)
	v_add_f32_e32 v96, v96, v98
	ds_bpermute_b32 v98, v147, v96
	s_waitcnt lgkmcnt(0)
	v_add_f32_e32 v96, v96, v98
	ds_bpermute_b32 v98, v148, v96
	s_waitcnt lgkmcnt(0)
	v_add_f32_e32 v96, v96, v98
	ds_bpermute_b32 v98, v149, v96
	s_waitcnt lgkmcnt(0)
	v_add_f32_e32 v96, v96, v98
	ds_bpermute_b32 v98, v150, v96
	s_waitcnt lgkmcnt(0)
	v_add_f32_e32 v96, v96, v98
	ds_bpermute_b32 v98, v151, v96
	s_waitcnt lgkmcnt(0)
	v_add_f32_e32 v96, v96, v98
	v_fmamk_f32 v96, v96, 0x3a000000, v228
	v_mul_f32_e32 v98, 0x4f800000, v96
	v_cmp_gt_f32_e32 vcc, s0, v96
	s_nop 1
	v_cndmask_b32_e32 v96, v96, v98, vcc
	v_sqrt_f32_e32 v98, v96
	s_nop 0
	v_add_u32_e32 v99, -1, v98
	v_fma_f32 v160, -v99, v98, v96
	v_cmp_ge_f32_e64 s[0:1], 0, v160
	v_add_u32_e32 v160, 1, v98
	s_nop 0
	v_cndmask_b32_e64 v99, v98, v99, s[0:1]
	v_fma_f32 v98, -v160, v98, v96
	v_cmp_lt_f32_e64 s[0:1], 0, v98
	s_nop 1
	v_cndmask_b32_e64 v98, v99, v160, s[0:1]
	v_mul_f32_e32 v99, 0x37800000, v98
	v_cndmask_b32_e32 v98, v98, v99, vcc
	v_cmp_class_f32_e32 vcc, v96, v229
	s_nop 1
	v_cndmask_b32_e32 v96, v98, v96, vcc
	v_div_scale_f32 v98, s[0:1], v96, v96, 1.0
	v_rcp_f32_e32 v99, v98
	s_mov_b64 s[0:1], 0x1000
	v_fma_f32 v160, -v98, v99, 1.0
	v_fmac_f32_e32 v99, v160, v99
	v_div_scale_f32 v160, vcc, 1.0, v96, 1.0
	v_mul_f32_e32 v161, v160, v99
	v_fma_f32 v162, -v98, v161, v160
	v_fmac_f32_e32 v161, v162, v99
	v_fma_f32 v98, -v98, v161, v160
	v_div_fmas_f32 v98, v98, v99, v161
	v_div_fixup_f32 v96, v98, v96, 1.0
	v_pk_mul_f32 v[12:13], v[12:13], v[96:97] op_sel_hi:[1,0]
	v_pk_mul_f32 v[14:15], v[14:15], v[96:97] op_sel_hi:[1,0]
	s_waitcnt vmcnt(8)
	v_pk_fma_f32 v[12:13], v[88:89], v[12:13], v[92:93]
	v_pk_fma_f32 v[14:15], v[90:91], v[14:15], v[94:95]
	v_cvt_pk_bf16_f32 v12, v12, v13
	v_cvt_pk_bf16_f32 v13, v14, v15
	v_pk_mul_f32 v[0:1], v[0:1], v[96:97] op_sel_hi:[1,0]
	v_pk_mul_f32 v[2:3], v[2:3], v[96:97] op_sel_hi:[1,0]
	v_pk_mul_f32 v[28:29], v[28:29], v[96:97] op_sel_hi:[1,0]
	v_pk_mul_f32 v[30:31], v[30:31], v[96:97] op_sel_hi:[1,0]
	v_pk_mul_f32 v[24:25], v[24:25], v[96:97] op_sel_hi:[1,0]
	v_pk_mul_f32 v[26:27], v[26:27], v[96:97] op_sel_hi:[1,0]
	v_pk_mul_f32 v[20:21], v[20:21], v[96:97] op_sel_hi:[1,0]
	v_pk_mul_f32 v[22:23], v[22:23], v[96:97] op_sel_hi:[1,0]
	global_store_dwordx2 v[142:143], v[12:13], off offset:1536
	v_pk_mul_f32 v[12:13], v[16:17], v[96:97] op_sel_hi:[1,0]
	v_pk_mul_f32 v[14:15], v[18:19], v[96:97] op_sel_hi:[1,0]
	v_pk_mul_f32 v[8:9], v[8:9], v[96:97] op_sel_hi:[1,0]
	v_pk_mul_f32 v[10:11], v[10:11], v[96:97] op_sel_hi:[1,0]
	v_pk_mul_f32 v[4:5], v[4:5], v[96:97] op_sel_hi:[1,0]
	v_pk_mul_f32 v[6:7], v[6:7], v[96:97] op_sel_hi:[1,0]
	s_waitcnt vmcnt(1)
; DI unsigned cvtpk(float lo, float hi) { f32x2 v = {lo, hi}; bf16x2_t b = __builtin_convertvector(v, bf16x2_t); return __builtin_bit_cast(unsigned, b); }
; template <int MODE, bool XBF> DI void norm_phase(const void* Xv, const bf16_t* Y, bf16_t* xr_out, float* xout, const float* __restrict__ lnw, const float* __restrict__ modl  , int sh_off, int sc_off, bf16_t* out_bf, int gw, int NGW, int lane) {
;     ...
;         if (b != curb) { curb = b;
; #pragma unroll
;             for (int j = 0; j < 8; ++j) { const int k = 4 * (lane + 64 * j); const f32x4 g = *(const f32x4*)(lnw + k);
;                 if (MODE == 0) { const f32x4 sc = *(const f32x4*)(modl + b * NMOD + sc_off + k); A[j] = g * (sc + 1.0f); B[j] = *(const f32x4*)(modl + b * NMOD + sh_off + k); } else { A[j] = g; B[j] = (f32x4){0.f, 0.f, 0.f, 0.f}; } } }
;     ...
;             u32x2* o = (u32x2*)(out_bf + (size_t)m * D) + lane;
; #pragma unroll
;             for (int j = 0; j < 8; ++j) { const f32x4 y = v[j] * rstd * A[j] + B[j]; u32x2 w; w.x = cvtpk(y.x, y.y); w.y = cvtpk(y.z, y.w); o[64 * j] = w; }
;         } else { f32x4* xo = (f32x4*)(xout + (size_t)m * D) + lane;
; #pragma unroll
;             for (int j = 0; j < 8; ++j) xo[64 * j] = v[j] * rstd * A[j]; }
; #pragma unroll
;         for (int j = 0; j < 8; ++j) { v[j] = vn[j]; yv[j] = yn[j]; xb[j] = xbn[j]; }
	v_pk_fma_f32 v[2:3], v[126:127], v[2:3], v[130:131]
	v_pk_fma_f32 v[0:1], v[124:125], v[0:1], v[128:129]
	v_pk_fma_f32 v[30:31], v[34:35], v[30:31], v[38:39]
	v_pk_fma_f32 v[28:29], v[32:33], v[28:29], v[36:37]
	v_pk_fma_f32 v[26:27], v[42:43], v[26:27], v[46:47]
	v_pk_fma_f32 v[24:25], v[40:41], v[24:25], v[44:45]
	v_pk_fma_f32 v[22:23], v[50:51], v[22:23], v[54:55]
	v_pk_fma_f32 v[20:21], v[48:49], v[20:21], v[52:53]
	v_pk_fma_f32 v[14:15], v[102:103], v[14:15], v[106:107]
	v_pk_fma_f32 v[12:13], v[100:101], v[12:13], v[104:105]
	v_pk_fma_f32 v[10:11], v[110:111], v[10:11], v[114:115]
	v_pk_fma_f32 v[8:9], v[108:109], v[8:9], v[112:113]
	v_pk_fma_f32 v[6:7], v[118:119], v[6:7], v[122:123]
	v_pk_fma_f32 v[4:5], v[116:117], v[4:5], v[120:121]
	v_cvt_pk_bf16_f32 v0, v0, v1
	v_cvt_pk_bf16_f32 v1, v2, v3
	v_cvt_pk_bf16_f32 v28, v28, v29
	v_cvt_pk_bf16_f32 v29, v30, v31
	v_cvt_pk_bf16_f32 v24, v24, v25
	v_cvt_pk_bf16_f32 v25, v26, v27
	v_cvt_pk_bf16_f32 v20, v20, v21
	v_cvt_pk_bf16_f32 v21, v22, v23
	v_cvt_pk_bf16_f32 v12, v12, v13
	v_cvt_pk_bf16_f32 v13, v14, v15
	v_cvt_pk_bf16_f32 v8, v8, v9
	v_cvt_pk_bf16_f32 v9, v10, v11
	v_cvt_pk_bf16_f32 v4, v4, v5
	v_cvt_pk_bf16_f32 v5, v6, v7
	global_store_dwordx2 v[142:143], v[0:1], off offset:3584
	v_mov_b64_e32 v[0:1], v[72:73]
	global_store_dwordx2 v[142:143], v[28:29], off
	global_store_dwordx2 v[142:143], v[24:25], off offset:512
	global_store_dwordx2 v[142:143], v[20:21], off offset:1024
	global_store_dwordx2 v[142:143], v[12:13], off offset:2048
	global_store_dwordx2 v[142:143], v[8:9], off offset:2560
	global_store_dwordx2 v[142:143], v[4:5], off offset:3072
	v_lshl_add_u64 v[142:143], v[142:143], 0, s[0:1]
	s_and_b64 vcc, exec, s[8:9]
	v_mov_b64_e32 v[2:3], v[74:75]
	v_mov_b32_e32 v28, v68
	v_mov_b32_e32 v29, v69
	v_mov_b32_e32 v30, v70
	v_mov_b32_e32 v31, v71
	v_mov_b32_e32 v24, v64
	v_mov_b32_e32 v25, v65
	v_mov_b32_e32 v26, v66
	v_mov_b32_e32 v27, v67
	v_mov_b32_e32 v20, v60
	v_mov_b32_e32 v21, v61
	v_mov_b32_e32 v22, v62
	v_mov_b32_e32 v23, v63
	v_mov_b32_e32 v12, v56
	v_mov_b32_e32 v13, v57
	v_mov_b32_e32 v14, v58
	v_mov_b32_e32 v15, v59
	v_mov_b32_e32 v16, v84
	v_mov_b32_e32 v17, v85
	v_mov_b32_e32 v18, v86
	v_mov_b32_e32 v19, v87
	v_mov_b32_e32 v8, v80
	v_mov_b32_e32 v9, v81
	v_mov_b32_e32 v10, v82
	v_mov_b32_e32 v11, v83
	v_mov_b32_e32 v4, v76
	v_mov_b32_e32 v5, v77
	v_mov_b32_e32 v6, v78
	v_mov_b32_e32 v7, v79
	v_mov_b32_e32 v96, v72
	v_mov_b32_e32 v98, v73
	v_mov_b32_e32 v99, v74
	v_mov_b32_e32 v160, v75
	s_cbranch_vccnz .LBB0_720
.LBB0_716:
	s_ashr_i32 s0, s4, 31
	s_lshr_b32 s0, s0, 19
	s_add_i32 s0, s4, s0
	s_ashr_i32 s5, s0, 13
	s_cmp_eq_u32 s5, s11
	s_cbranch_scc1 .LBB0_718
	s_mul_i32 s0, s5, 0x3000
	s_ashr_i32 s1, s0, 31
	s_lshl_b64 s[0:1], s[0:1], 2
	v_readlane_b32 s8, v255, 0
	s_add_u32 s0, s8, s0
	v_readlane_b32 s8, v255, 1
	s_addc_u32 s1, s8, s1
	s_add_u32 s8, s0, 0x2000
	s_addc_u32 s9, s1, 0
	s_mov_b32 s11, s5
	s_nop 1
	global_load_dwordx4 v[32:35], v[132:133], off
	global_load_dwordx4 v[36:39], v152, s[8:9]
	global_load_dwordx4 v[40:43], v[132:133], off offset:1024
	global_load_dwordx4 v[44:47], v153, s[8:9]
	global_load_dwordx4 v[48:51], v[132:133], off offset:2048
	global_load_dwordx4 v[52:55], v154, s[8:9]
	global_load_dwordx4 v[88:91], v[132:133], off offset:3072
	global_load_dwordx4 v[92:95], v155, s[8:9]
	global_load_dwordx4 v[100:103], v[134:135], off
	global_load_dwordx4 v[104:107], v156, s[8:9]
	global_load_dwordx4 v[108:111], v[136:137], off
	global_load_dwordx4 v[112:115], v157, s[8:9]
	global_load_dwordx4 v[116:119], v[138:139], off
	global_load_dwordx4 v[120:123], v158, s[8:9]
	global_load_dwordx4 v[124:127], v[140:141], off
	global_load_dwordx4 v[128:131], v159, s[8:9]
	s_waitcnt vmcnt(0)
	v_pk_add_f32 v[38:39], v[38:39], 1.0 op_sel_hi:[1,0]
	v_pk_add_f32 v[36:37], v[36:37], 1.0 op_sel_hi:[1,0]
	v_pk_mul_f32 v[34:35], v[34:35], v[38:39]
	v_pk_mul_f32 v[32:33], v[32:33], v[36:37]
	v_pk_add_f32 v[46:47], v[46:47], 1.0 op_sel_hi:[1,0]
	v_pk_add_f32 v[44:45], v[44:45], 1.0 op_sel_hi:[1,0]
	v_pk_mul_f32 v[42:43], v[42:43], v[46:47]
	v_pk_mul_f32 v[40:41], v[40:41], v[44:45]
	v_pk_add_f32 v[54:55], v[54:55], 1.0 op_sel_hi:[1,0]
	v_pk_add_f32 v[52:53], v[52:53], 1.0 op_sel_hi:[1,0]
	v_pk_mul_f32 v[50:51], v[50:51], v[54:55]
	v_pk_mul_f32 v[48:49], v[48:49], v[52:53]
	v_pk_add_f32 v[94:95], v[94:95], 1.0 op_sel_hi:[1,0]
	v_pk_add_f32 v[92:93], v[92:93], 1.0 op_sel_hi:[1,0]
	v_pk_mul_f32 v[90:91], v[90:91], v[94:95]
	v_pk_mul_f32 v[88:89], v[88:89], v[92:93]
	v_pk_add_f32 v[106:107], v[106:107], 1.0 op_sel_hi:[1,0]
	v_pk_add_f32 v[104:105], v[104:105], 1.0 op_sel_hi:[1,0]
	v_pk_mul_f32 v[102:103], v[102:103], v[106:107]
	v_pk_mul_f32 v[100:101], v[100:101], v[104:105]
	v_pk_add_f32 v[114:115], v[114:115], 1.0 op_sel_hi:[1,0]
	v_pk_add_f32 v[112:113], v[112:113], 1.0 op_sel_hi:[1,0]
	v_pk_mul_f32 v[110:111], v[110:111], v[114:115]
	v_pk_mul_f32 v[108:109], v[108:109], v[112:113]
	v_pk_add_f32 v[122:123], v[122:123], 1.0 op_sel_hi:[1,0]
	v_pk_add_f32 v[120:121], v[120:121], 1.0 op_sel_hi:[1,0]
	v_pk_mul_f32 v[118:119], v[118:119], v[122:123]
	v_pk_mul_f32 v[116:117], v[116:117], v[120:121]
	v_pk_add_f32 v[130:131], v[130:131], 1.0 op_sel_hi:[1,0]
	v_pk_add_f32 v[128:129], v[128:129], 1.0 op_sel_hi:[1,0]
	v_pk_mul_f32 v[126:127], v[126:127], v[130:131]
	v_pk_mul_f32 v[124:125], v[124:125], v[128:129]
	global_load_dwordx4 v[36:39], v152, s[0:1]
	global_load_dwordx4 v[44:47], v152, s[0:1] offset:1024
	global_load_dwordx4 v[52:55], v152, s[0:1] offset:2048
	global_load_dwordx4 v[92:95], v152, s[0:1] offset:3072
	global_load_dwordx4 v[104:107], v156, s[0:1]
	global_load_dwordx4 v[112:115], v157, s[0:1]
	global_load_dwordx4 v[120:123], v158, s[0:1]
	global_load_dwordx4 v[128:131], v159, s[0:1]
	s_add_i32 s0, s4, 1
	s_cmp_ge_i32 s0, s10
	s_cbranch_scc0 .Lrl_bb_717
	s_waitcnt vmcnt(0)
.Lrl_bb_717:
.LBB0_718:
	s_add_i32 s4, s4, 1
	s_cmp_ge_i32 s4, s10
	s_cselect_b64 s[8:9], -1, 0
	s_and_b64 vcc, exec, s[8:9]
	s_cbranch_vccnz .LBB0_715
	v_add_co_u32_e32 v72, vcc, 0x1000, v144
	global_load_dwordx4 v[68:71], v[144:145], off
	global_load_dwordx4 v[64:67], v[144:145], off offset:1024
	global_load_dwordx4 v[60:63], v[144:145], off offset:2048
	global_load_dwordx4 v[56:59], v[144:145], off offset:3072
	v_addc_co_u32_e32 v73, vcc, 0, v145, vcc
	global_load_dwordx4 v[84:87], v[72:73], off
	global_load_dwordx4 v[80:83], v[72:73], off offset:1024
	global_load_dwordx4 v[76:79], v[72:73], off offset:2048
	s_nop 0
	global_load_dwordx4 v[72:75], v[72:73], off offset:3072
	s_branch .LBB0_715
